# v18 + phase-0 load balancing: position-table units 512..575 moved from workgroups 0..63 (three units) to workgroups 192..255 (two short units)
# speedup vs baseline: 1.0039x; 1.0039x over previous
.LBB0_9:
	s_add_i32 s75, s75, s56
	s_cmp_eq_u32 s56, 0x100
	s_cbranch_scc0 .Lp0_norm
	s_sub_i32 s98, s75, 0x200
	s_cmp_lt_u32 s98, 64
	s_cbranch_scc1 .LBB0_63
	s_sub_i32 s98, s75, 0x2c0
	s_cmp_lt_u32 s98, 64
	s_cbranch_scc0 .Lp0_norm
	s_add_i32 s75, s98, 0x200
.Lp0_norm:
	s_cmpk_lt_i32 s75, 0x240
	s_cbranch_scc0 .LBB0_63
